# XCD barrier: the workgroup completing the top level bumps all XGEN words itself; per-XCD leaders no longer re-publish after seeing TOPGEN (on top of early acquire)
# baseline (speedup 1.0000x reference)
; __device__ __forceinline__ unsigned xb_ld(unsigned* p)              { return __hip_atomic_load(p, __ATOMIC_RELAXED, __HIP_MEMORY_SCOPE_AGENT); }
; __device__ __forceinline__ unsigned xb_add(unsigned* p, unsigned v) { return __hip_atomic_fetch_add(p, v, __ATOMIC_RELAXED, __HIP_MEMORY_SCOPE_AGENT); }
; #define XB_SPIN(cond, bar) do { unsigned _sp = 0; while (cond) { __builtin_amdgcn_s_sleep(1); \
;     if ((++_sp & 255u) == 0u) { if (xb_ld(&(bar)[XB_TMO])) break; if (_sp > XB_SPIN_CAP) { atomicAdd(&(bar)[XB_TMO], 1u); break; } } } } while (0)
; __device__ __forceinline__ void xcd_barrier(const XcdBarrier& b) {
;     ...
;             const unsigned og = xb_add(&bar[XB_TOP], 1u);
;             const unsigned tg = og / nx;
;             if (og + 1u == (tg + 1u) * nx) xb_add(&bar[XB_TOPGEN], 1u);
;             else XB_SPIN(xb_ld(&bar[XB_TOPGEN]) == tg, bar);
;             __builtin_amdgcn_fence(__ATOMIC_ACQUIRE, "agent");
;             xb_add(&bar[XB_XGEN(b.x)], 1u);
;             asm volatile("s_waitcnt vmcnt(0)" ::: "memory");
.Lxs0_134:
	s_or_b64 exec, exec, s[4:5]
	s_and_saveexec_b64 s[4:5], s[8:9]
	s_cbranch_execz .Lxs0_136
	v_mov_b32_e32 v2, 1
	global_atomic_add v[0:1], v2, off
	v_cmp_eq_u32_e32 vcc, s6, v0
	s_and_saveexec_b64 s[10:11], vcc
	v_add_co_u32_e32 v4, vcc, 0xffffef00, v0
	s_nop 1
	v_addc_co_u32_e32 v5, vcc, -1, v1, vcc
	global_atomic_add v[4:5], v2, off
	global_atomic_add v[4:5], v2, off offset:256
	global_atomic_add v[4:5], v2, off offset:512
	global_atomic_add v[4:5], v2, off offset:768
	global_atomic_add v[4:5], v2, off offset:1024
	global_atomic_add v[4:5], v2, off offset:1280
	global_atomic_add v[4:5], v2, off offset:1536
	global_atomic_add v[4:5], v2, off offset:1792
	global_atomic_add v[4:5], v2, off offset:2048
	global_atomic_add v[4:5], v2, off offset:2304
	global_atomic_add v[4:5], v2, off offset:2560
	global_atomic_add v[4:5], v2, off offset:2816
	global_atomic_add v[4:5], v2, off offset:3072
	global_atomic_add v[4:5], v2, off offset:3328
	global_atomic_add v[4:5], v2, off offset:3584
	global_atomic_add v[4:5], v2, off offset:3840
	s_or_b64 exec, exec, s[10:11]
.Lxs0_136:
	s_or_b64 exec, exec, s[4:5]
	s_mov_b64 s[4:5], exec
	v_mbcnt_lo_u32_b32 v0, s4, 0
	v_mbcnt_hi_u32_b32 v0, s5, v0
	v_cmp_eq_u32_e32 vcc, 0, v0
	s_waitcnt vmcnt(0)
	s_nop 0
	s_and_saveexec_b64 s[6:7], vcc
	s_cbranch_execz .Lxs0_138
	s_bcnt1_i32_b64 s4, s[4:5]
	v_mov_b32_e32 v0, 0x2000
	v_mov_b32_e32 v1, s4
	s_nop 0
